# weight transposes moved from phase 0 into phase 1, half the blocks before / half after the filter units (stream/compute overlap)
# speedup vs baseline: 1.0129x; 1.0129x over previous
.LBB0_130:
	s_or_b64 exec, exec, s[0:1]
	s_branch .LBB0_154

.LBB0_231:
	s_or_b64 exec, exec, s[0:1]
	s_cmp_lt_u32 s96, 128
	s_cbranch_scc1 .Ltrp1_A_skip
	s_load_dwordx2 s[0:1], s[92:93], 0x58
	s_load_dwordx2 s[2:3], s[92:93], 0xb8
	s_load_dwordx2 s[4:5], s[92:93], 0xc0
	s_load_dwordx2 s[6:7], s[92:93], 0xc8
	s_load_dwordx2 s[8:9], s[92:93], 0xd0
	s_load_dwordx2 s[10:11], s[92:93], 0xe8
	v_and_b32_e32 v74, 63, v154
	v_lshrrev_b32_e32 v75, 6, v154
	v_mul_u32_u24_e32 v75, 0x2100, v75
	v_lshrrev_b32_e32 v3, 5, v74
	v_and_b32_e32 v4, 31, v74
	v_lshlrev_b32_e32 v4, 2, v4
	v_lshrrev_b32_e32 v5, 3, v74
	v_and_b32_e32 v6, 7, v74
	v_mul_u32_u24_e32 v2, 264, v6
	v_add_u32_e32 v2, v2, v5
	v_lshl_add_u32 v2, v2, 2, v75
	v_lshlrev_b32_e32 v6, 4, v6
	v_mul_u32_u24_e32 v1, 132, v5
	v_add3_u32 v1, v1, v6, v75
	v_readfirstlane_b32 s13, v154
	s_lshr_b32 s13, s13, 6
	s_lshl_b32 s26, s96, 3
	s_add_u32 s13, s13, s26
	s_mov_b32 s12, s13
	s_waitcnt lgkmcnt(0)
	s_cmp_ge_u32 s12, 44544
	s_cbranch_scc1 .Ltrb_done
	s_cmp_ge_u32 s12, 33280
	s_cselect_b32 s41, 1, 0
	s_cselect_b32 s26, 33280, 0
	s_sub_u32 s42, s12, s26
	s_cmp_ge_u32 s42, 12288
	s_cbranch_scc1 .Ltrb_m2
	s_mul_i32 s43, s42, 43691
	s_lshr_b32 s43, s43, 24
	s_mul_i32 s26, s43, 384
	s_sub_u32 s44, s42, s26
	s_mov_b32 s14, s0
	s_mov_b32 s15, s1
	s_mov_b32 s36, 0xc000
	s_mov_b32 s37, 0x6000000
	s_mov_b32 s38, 0x0
	s_mov_b32 s39, 0x3000000
	s_mov_b32 s40, 0x1000
	s_branch .Ltrb_dec_done1

.Ltrb_done:
	s_waitcnt vmcnt(0) lgkmcnt(0)
	s_branch .Ltrp1_A_done
.Ltrp1_A_done:
	s_barrier
.Ltrp1_A_skip:
	v_mov_b32_e32 v2, v154
	s_mov_b32 s20, s96
	s_cmpk_gt_i32 s20, 0x1ff
	s_cbranch_scc1 .Ltrp1_B
	v_lshlrev_b32_e32 v5, 8, v2
	v_bfe_u32 v4, v2, 3, 1
	v_and_b32_e32 v5, 0x400, v5
	v_lshl_or_b32 v7, v4, 11, v5
	v_lshlrev_b32_e32 v38, 10, v4
	v_ashrrev_i32_e32 v4, 8, v2
	v_bfe_u32 v3, v2, 4, 2
	v_ashrrev_i32_e32 v5, 31, v4
	v_and_b32_e32 v37, 3, v2
	v_lshlrev_b32_e32 v9, 15, v4
	v_lshlrev_b64 v[18:19], 10, v[4:5]
	v_lshlrev_b32_e32 v4, 15, v3
	v_ashrrev_i32_e32 v36, 6, v2
	v_or3_b32 v41, v4, v37, v7
	v_or3_b32 v4, v7, v37, v4
	v_or_b32_e32 v42, 0x20000, v4
	v_or_b32_e32 v43, 0x21000, v4
	v_or_b32_e32 v44, 0x22000, v4
	v_or_b32_e32 v45, 0x23000, v4
	v_or_b32_e32 v46, 0x24000, v4
	v_or_b32_e32 v47, 0x25000, v4
	v_or_b32_e32 v48, 0x26000, v4
	v_or_b32_e32 v49, 0x27000, v4
	v_lshlrev_b32_e32 v4, 4, v36
	v_and_b32_e32 v6, 15, v2
	v_lshl_or_b32 v50, v3, 2, v4
	v_and_b32_e32 v3, 0xffffffc0, v2
	v_lshl_add_u32 v3, v6, 12, v3
	v_and_b32_e32 v1, 63, v2
	v_and_b32_e32 v8, 3, v36
	v_and_or_b32 v3, v2, 48, v3
	v_lshlrev_b32_e32 v2, 1, v2
	v_lshlrev_b32_e32 v40, 12, v8
	v_and_b32_e32 v20, 0x60, v2
	v_mov_b32_e32 v21, 0
	v_add_u32_e32 v51, 0, v3
	v_lshl_add_u64 v[2:3], s[90:91], 0, v[20:21]
	s_mov_b64 s[2:3], 0x10478080
	v_ashrrev_i32_e32 v25, 31, v4
	v_or_b32_e32 v24, v4, v6
	v_or_b32_e32 v4, v9, v40
	v_lshlrev_b32_e32 v5, 2, v1
	s_load_dwordx4 s[4:7], s[92:93], 0xa0
	v_lshl_add_u64 v[22:23], v[2:3], 0, s[2:3]
	v_or_b32_e32 v2, v4, v5
	v_lshlrev_b32_e32 v20, 1, v1
	v_add_u32_e32 v52, 0, v2
	v_lshl_add_u64 v[2:3], s[90:91], 0, v[20:21]
	s_mov_b64 s[2:3], 0x10518000
	v_lshl_add_u64 v[26:27], v[2:3], 0, s[2:3]
	v_sub_u32_e32 v2, v4, v5
	v_add_u32_e32 v54, 0, v2
	v_mbcnt_lo_u32_b32 v2, -1, 0
	s_mov_b32 s1, 0
	v_add_u32_e32 v39, 0, v9
	v_or_b32_e32 v18, v18, v8
	s_movk_i32 s21, 0x4000
	v_add_u32_e32 v53, 0x4000, v52
	v_sub_u32_e32 v55, 0, v1
	s_mov_b32 s22, 0x8000
	s_mov_b32 s23, 0xc000
	s_mov_b32 s24, 0x10000
	s_mov_b32 s25, 0x14000
	s_mov_b32 s26, 0x18000
	s_mov_b32 s27, 0x1c000
	v_mov_b32_e32 v56, 0x500
	v_mov_b32_e32 v57, 0xa00000
	s_movk_i32 s28, 0x100
	s_mov_b64 s[2:3], 0x8000
	s_mov_b64 s[8:9], 0x80
	v_mbcnt_hi_u32_b32 v58, -1, v2
	s_branch .LBB0_234

.Ltrp1_B:
	s_cmp_ge_u32 s96, 128
	s_cbranch_scc1 .LBB0_257
	s_load_dwordx2 s[0:1], s[92:93], 0x58
	s_load_dwordx2 s[2:3], s[92:93], 0xb8
	s_load_dwordx2 s[4:5], s[92:93], 0xc0
	s_load_dwordx2 s[6:7], s[92:93], 0xc8
	s_load_dwordx2 s[8:9], s[92:93], 0xd0
	s_load_dwordx2 s[10:11], s[92:93], 0xe8
	v_and_b32_e32 v74, 63, v154
	v_lshrrev_b32_e32 v75, 6, v154
	v_mul_u32_u24_e32 v75, 0x2100, v75
	v_lshrrev_b32_e32 v3, 5, v74
	v_and_b32_e32 v4, 31, v74
	v_lshlrev_b32_e32 v4, 2, v4
	v_lshrrev_b32_e32 v5, 3, v74
	v_and_b32_e32 v6, 7, v74
	v_mul_u32_u24_e32 v2, 264, v6
	v_add_u32_e32 v2, v2, v5
	v_lshl_add_u32 v2, v2, 2, v75
	v_lshlrev_b32_e32 v6, 4, v6
	v_mul_u32_u24_e32 v1, 132, v5
	v_add3_u32 v1, v1, v6, v75
	v_readfirstlane_b32 s13, v154
	s_lshr_b32 s13, s13, 6
	s_lshl_b32 s26, s96, 3
	s_add_u32 s13, s13, s26
	s_mov_b32 s12, s13
	s_waitcnt lgkmcnt(0)
	s_cmp_ge_u32 s12, 44544
	s_cbranch_scc1 .Ltrc_done
	s_cmp_ge_u32 s12, 33280
	s_cselect_b32 s41, 1, 0
	s_cselect_b32 s26, 33280, 0
	s_sub_u32 s42, s12, s26
	s_cmp_ge_u32 s42, 12288
	s_cbranch_scc1 .Ltrc_m2
	s_mul_i32 s43, s42, 43691
	s_lshr_b32 s43, s43, 24
	s_mul_i32 s26, s43, 384
	s_sub_u32 s44, s42, s26
	s_mov_b32 s14, s0
	s_mov_b32 s15, s1
	s_mov_b32 s36, 0xc000
	s_mov_b32 s37, 0x6000000
	s_mov_b32 s38, 0x0
	s_mov_b32 s39, 0x3000000
	s_mov_b32 s40, 0x1000
	s_branch .Ltrc_dec_done1

.Ltrc_done:
	s_waitcnt vmcnt(0) lgkmcnt(0)
	s_branch .LBB0_257
.LBB0_257:
	s_cmp_gt_i32 s87, 2
	s_cbranch_scc1 .LBB0_357
	s_load_dword s0, s[92:93], 0x104
	s_waitcnt lgkmcnt(0)
	s_cmp_lt_i32 s0, 3
	s_cbranch_scc1 .LBB0_357
	s_cmp_eq_u32 s87, 2
	s_cbranch_scc1 .LBB0_327
	s_cmp_lt_u32 s0, 23
	s_mov_b64 s[0:1], -1
	s_cbranch_scc0 .LBB0_314
	s_getreg_b32 s2, hwreg(HW_REG_XCC_ID, 0, 4)
	s_waitcnt vmcnt(0)
	s_barrier
	s_mov_b64 s[0:1], exec
	v_readlane_b32 s4, v232, 4
	v_readlane_b32 s5, v232, 5
	s_and_b64 s[4:5], s[0:1], s[4:5]
	s_mov_b64 exec, s[4:5]
	s_cbranch_execz .LBB0_313
	s_add_i32 s3, 0, 0x20000
	v_mov_b32_e32 v1, s3
	s_waitcnt vmcnt(0) expcnt(0) lgkmcnt(0)
	ds_read_b32 v3, v1
	s_add_i32 s3, 0, 0x20004
	v_mov_b32_e32 v1, s3
	ds_read_b32 v1, v1
	s_and_b32 s33, s2, 15
	s_waitcnt lgkmcnt(1)
	v_cmp_ne_u32_e32 vcc, 0, v3
	s_cbranch_vccnz .LBB0_277
	s_add_u32 s2, s90, 0x2c918200
	s_addc_u32 s3, s91, 0
	s_add_u32 s4, s90, 0x2c918400
	s_addc_u32 s5, s91, 0
	s_add_u32 s6, s90, 0x2c918500
	s_addc_u32 s7, s91, 0
	s_add_u32 s8, s90, 0x2c918600
	s_addc_u32 s9, s91, 0
	s_add_u32 s10, s90, 0x2c918700
	s_addc_u32 s11, s91, 0
	s_add_u32 s12, s90, 0x2c918800
	s_addc_u32 s13, s91, 0
	s_add_u32 s14, s90, 0x2c918900
	s_addc_u32 s15, s91, 0
	s_add_u32 s16, s90, 0x2c918a00
	s_addc_u32 s17, s91, 0
	s_add_u32 s18, s90, 0x2c918b00
	s_addc_u32 s19, s91, 0
	s_add_u32 s20, s90, 0x2c918c00
	s_addc_u32 s21, s91, 0
	s_add_u32 s22, s90, 0x2c918d00
	s_addc_u32 s23, s91, 0
	s_add_u32 s24, s90, 0x2c918e00
	s_addc_u32 s25, s91, 0
	s_add_u32 s26, s90, 0x2c918f00
	s_addc_u32 s27, s91, 0
	s_add_u32 s28, s90, 0x2c919000
	s_addc_u32 s29, s91, 0
	s_add_u32 s30, s90, 0x2c919100
	s_addc_u32 s31, s91, 0
	s_add_u32 s34, s90, 0x2c919200
	s_addc_u32 s35, s91, 0
	s_mul_i32 s44, s95, s97
	s_add_u32 s36, s90, 0x2c919300
	s_mul_i32 s44, s44, s94
	s_addc_u32 s37, s91, 0
	s_mov_b32 s45, 1
	v_mov_b32_e32 v17, 0
	s_branch .LBB0_265
